# v30 + non-temporal policy on the coalesced f32 K/V cache stream of the sample attention units (read once)
# speedup vs baseline: 1.0158x; 1.0158x over previous
; #define GASP __attribute__((address_space(1)))
;     ...
;     { const bf16_t* qp = QB + (size_t)(rowq0 + r) * 512 + h * 128 + map * 64 + hi * 8;
; #pragma unroll
;       for (int d0 = 0; d0 < 4; ++d0) qf[d0] = *(const GASP bf16x8*)(qp + d0 * 16); }
;     f32x16 OT[NEB];
; #pragma unroll
;     for (int e = 0; e < NEB; ++e)
; #pragma unroll
;         for (int i = 0; i < 16; ++i) OT[e][i] = 0.f;
;     float m = -1e30f, l = 0.f;
;     const int lkey = tid >> 3, lc = tid & 7;
;     u32x4 pfA[NPF], pfB[SAMPLE ? 1 : NPF];
;     const float* ck = p.in[2]; const float* cv = p.in[3];
;     ...
;     const int i16 = lane & 15;
;     const int vlane_off = (4 * hi + (i16 >> 2)) * DA_VRS + (16 * ((lane >> 4) & 1) + 4 * (i16 & 3)) * 2;
;     const int tq = qpos0 + r;
;     ...
;     DA_ISSUE(pfA, 0); DA_WRITE(pfA, 0, 0);
;     if constexpr (SAMPLE) {
;         asm volatile("" : "+v"(qf[0]), "+v"(qf[1]), "+v"(qf[2]), "+v"(qf[3]));
;         __syncthreads();
; #pragma unroll 1
;         for (int tt = 0; tt < NT; ++tt) {
;             if (tt + 1 < NT) DA_ISSUE(pfA, tt + 1);
;             DA_COMPUTE(tt, tt & 1);
;             if (tt + 1 < NT) DA_WRITE(pfA, tt + 1, (tt + 1) & 1);
;             __syncthreads();
.LBB0_945:
	s_andn2_b64 vcc, exec, s[6:7]
	s_cbranch_vccnz .LBB0_869
	s_ashr_i32 s5, s4, 2
	v_mov_b32_e32 v0, v208
	s_lshl_b32 s56, s5, 5
	s_waitcnt vmcnt(4)
	v_ashrrev_i32_e32 v18, 3, v0
	s_lshl_b32 s41, s5, 12
	s_and_b32 s8, s4, 3
	v_and_b32_e32 v175, 31, v0
	s_add_i32 s4, s56, 0x8000
	v_add_u32_e32 v4, s41, v18
	v_or_b32_e32 v162, s4, v175
	s_lshl_b32 s4, s8, 7
	v_and_b32_e32 v8, 7, v0
	v_ashrrev_i32_e32 v5, 31, v4
	v_lshlrev_b64 v[4:5], 11, v[4:5]
	v_lshl_or_b32 v164, v8, 4, s4
	v_lshl_or_b32 v242, v8, 2, s4
	v_lshlrev_b32_e32 v243, 3, v8
	v_readfirstlane_b32 s33, v0
	v_ashrrev_i32_e32 v163, 31, v162
	v_lshl_or_b32 v4, v164, 2, v4
	s_ashr_i32 s40, s33, 8
	v_lshlrev_b64 v[2:3], 10, v[162:163]
	v_lshl_add_u64 v[6:7], s[24:25], 0, v[4:5]
	v_lshl_add_u64 v[4:5], s[26:27], 0, v[4:5]
	global_load_dwordx4 v[112:115], v[6:7], off offset:16
	global_load_dwordx4 v[116:119], v[6:7], off
	v_lshl_add_u64 v[2:3], s[70:71], 0, v[2:3]
	s_lshl_b32 s30, s8, 8
	global_load_dwordx4 v[120:123], v[6:7], off offset:48
	global_load_dwordx4 v[124:127], v[6:7], off offset:32
	global_load_dwordx4 v[128:131], v[4:5], off offset:16
	global_load_dwordx4 v[136:139], v[4:5], off
	s_lshl_b32 s6, s40, 6
	global_load_dwordx4 v[132:135], v[4:5], off offset:48
	global_load_dwordx4 v[140:143], v[4:5], off offset:32
	v_bfe_u32 v176, v0, 5, 1
	v_lshl_add_u64 v[2:3], v[2:3], 0, s[30:31]
	s_ashr_i32 s7, s6, 31
	v_lshl_add_u64 v[2:3], s[6:7], 1, v[2:3]
	v_lshlrev_b32_e32 v166, 4, v176
	v_mov_b32_e32 v167, v1
	v_lshl_add_u64 v[2:3], v[2:3], 0, v[166:167]
	global_load_dwordx4 v[144:147], v[2:3], off offset:96
	global_load_dwordx4 v[148:151], v[2:3], off offset:64
	global_load_dwordx4 v[152:155], v[2:3], off offset:32
	global_load_dwordx4 v[156:159], v[2:3], off
	s_not_b32 s5, s8
	v_lshrrev_b32_e32 v2, 2, v0
	v_and_b32_e32 v3, 16, v0
	v_lshlrev_b32_e32 v4, 2, v0
	v_bfe_u32 v5, v0, 2, 1
	v_lshlrev_b32_e32 v0, 5, v0
	s_movk_i32 s6, 0x2400
	s_lshl_b32 s5, s5, 1
	v_lshlrev_b32_e32 v167, 2, v176
	v_and_or_b32 v3, v4, 12, v3
	v_mad_u32_u24 v4, v5, s6, 0
	v_mul_lo_u32 v177, v18, s90
	v_and_b32_e32 v178, 0x60, v0
	v_ldexp_f32 v6, 1.0, s5
	v_mul_u32_u24_e32 v169, 0x2400, v5
	v_mul_lo_u32 v179, v18, s88
	v_lshlrev_b32_e32 v180, 5, v8
	v_and_or_b32 v0, v2, 3, v167
	v_lshlrev_b32_e32 v182, 1, v3
	v_add3_u32 v19, v4, v177, v178
	v_mul_f32_e32 v181, 0x3fb8aa3b, v6
	v_add3_u32 v20, 0, v179, v180
	v_mul_u32_u24_e32 v183, 0x140, v0
	v_readfirstlane_b32 s8, v181
	v_add_u32_e32 v186, 64, v18
	v_mov_b32_e32 v0, v1
	s_lshr_b32 s5, s33, 6
	s_bfe_u32 s30, s33, 0x20006
	s_lshl_b32 s98, s40, 1
	s_xor_b32 s30, s30, s98
	s_addk_i32 s56, 0x7000
	v_mul_u32_u24_e32 v184, 0x90, v175
	s_mov_b32 s9, s8
	s_mov_b32 s57, s8
	s_mov_b32 s84, s8
	s_mov_b32 s85, s8
	s_mov_b32 s86, s8
	s_mov_b32 s87, s8
	s_mov_b32 s91, s8
	s_mov_b32 s92, s8
	s_mov_b32 s93, s8
	s_mov_b32 s94, s8
	s_mov_b32 s95, s8
	s_mov_b32 s96, s8
	s_mov_b32 s97, s8
	s_mov_b32 s14, s8
	s_mov_b32 s15, s8
	v_sub_u32_e32 v185, v175, v167
	s_mov_b32 s34, 0
	v_mov_b32_e32 v168, 0xf149f2ca
	v_mov_b32_e32 v187, 0
	s_mov_b32 s28, 0
	s_waitcnt vmcnt(11)
	v_cvt_pk_bf16_f32 v4, v112, v113
	s_waitcnt vmcnt(10)
	v_cvt_pk_bf16_f32 v2, v116, v117
	v_cvt_pk_bf16_f32 v3, v118, v119
	v_cvt_pk_bf16_f32 v5, v114, v115
	s_waitcnt vmcnt(8)
	v_cvt_pk_bf16_f32 v6, v124, v125
	v_cvt_pk_bf16_f32 v7, v126, v127
	v_cvt_pk_bf16_f32 v8, v120, v121
	s_waitcnt vmcnt(4)
	v_cvt_pk_bf16_f32 v14, v140, v141
	v_cvt_pk_bf16_f32 v15, v142, v143
	v_cvt_pk_bf16_f32 v9, v122, v123
	v_cvt_pk_bf16_f32 v10, v136, v137
	v_cvt_pk_bf16_f32 v11, v138, v139
	v_cvt_pk_bf16_f32 v12, v128, v129
	v_cvt_pk_bf16_f32 v13, v130, v131
	v_cvt_pk_bf16_f32 v16, v132, v133
	v_cvt_pk_bf16_f32 v17, v134, v135
	ds_write_b128 v19, v[2:5]
	ds_write_b128 v19, v[6:9] offset:16
	ds_write_b128 v20, v[10:13] offset:18432
	ds_write_b128 v20, v[14:17] offset:18448
	v_mov_b32_e32 v14, v1
	v_mov_b32_e32 v15, v1
	v_mov_b32_e32 v2, v1
	v_mov_b32_e32 v3, v1
	v_mov_b32_e32 v4, v1
	v_mov_b32_e32 v5, v1
	v_mov_b32_e32 v6, v1
	v_mov_b32_e32 v7, v1
	v_mov_b32_e32 v8, v1
	v_mov_b32_e32 v9, v1
	v_mov_b32_e32 v10, v1
	v_mov_b32_e32 v11, v1
	v_mov_b32_e32 v12, v1
	v_mov_b32_e32 v13, v1
	v_mov_b64_e32 v[30:31], v[14:15]
	v_mov_b64_e32 v[46:47], v[14:15]
	v_mov_b64_e32 v[62:63], v[14:15]
	v_mov_b64_e32 v[78:79], v[14:15]
	v_mov_b64_e32 v[28:29], v[12:13]
	v_mov_b64_e32 v[26:27], v[10:11]
	v_mov_b64_e32 v[24:25], v[8:9]
	v_mov_b64_e32 v[22:23], v[6:7]
	v_mov_b64_e32 v[20:21], v[4:5]
	v_mov_b64_e32 v[18:19], v[2:3]
	v_mov_b64_e32 v[16:17], v[0:1]
	v_mov_b64_e32 v[44:45], v[12:13]
	v_mov_b64_e32 v[42:43], v[10:11]
	v_mov_b64_e32 v[40:41], v[8:9]
	v_mov_b64_e32 v[38:39], v[6:7]
	v_mov_b64_e32 v[36:37], v[4:5]
	v_mov_b64_e32 v[34:35], v[2:3]
	v_mov_b64_e32 v[32:33], v[0:1]
	v_mov_b64_e32 v[60:61], v[12:13]
	v_mov_b64_e32 v[58:59], v[10:11]
	v_mov_b64_e32 v[56:57], v[8:9]
	v_mov_b64_e32 v[54:55], v[6:7]
	v_mov_b64_e32 v[52:53], v[4:5]
	v_mov_b64_e32 v[50:51], v[2:3]
	v_mov_b64_e32 v[48:49], v[0:1]
	v_mov_b64_e32 v[76:77], v[12:13]
	v_mov_b64_e32 v[74:75], v[10:11]
	v_mov_b64_e32 v[72:73], v[8:9]
	v_mov_b64_e32 v[70:71], v[6:7]
	v_mov_b64_e32 v[68:69], v[4:5]
	v_mov_b64_e32 v[66:67], v[2:3]
	v_mov_b64_e32 v[64:65], v[0:1]
	s_waitcnt vmcnt(0)
	s_waitcnt lgkmcnt(0)
	s_barrier
	v_add_u32_e32 v2, s41, v186
	v_ashrrev_i32_e32 v3, 31, v2
	v_lshlrev_b64 v[2:3], 11, v[2:3]
	v_lshl_or_b32 v2, v242, 2, v2
	v_lshl_add_u64 v[4:5], s[24:25], 0, v[2:3]
	v_lshl_add_u64 v[2:3], s[26:27], 0, v[2:3]
	global_load_dwordx4 v[218:221], v[4:5], off offset:384 nt
	global_load_dwordx4 v[222:225], v[4:5], off offset:256 nt
	global_load_dwordx4 v[210:213], v[4:5], off offset:128 nt
	global_load_dwordx4 v[214:217], v[4:5], off nt
	global_load_dwordx4 v[230:233], v[2:3], off offset:384 nt
	global_load_dwordx4 v[238:241], v[2:3], off offset:256 nt
	global_load_dwordx4 v[226:229], v[2:3], off offset:128 nt
	global_load_dwordx4 v[234:237], v[2:3], off nt
	v_add_u32_e32 v186, 64, v186
.LBB0_947:
	s_cmpk_eq_i32 s34, 0xf000
	s_cselect_b64 s[6:7], -1, 0
	s_cmpk_lg_i32 s34, 0xf000
	s_cselect_b64 s[10:11], -1, 0
	s_cmp_gt_u32 s28, 62
	s_cbranch_scc1 .Ls2_issue_done
	s_bitcmp1_b32 s28, 0
	s_cbranch_scc1 .Ls2_issue_odd
	s_cmp_eq_u32 s28, 62
	s_cbranch_scc1 .Ls2_issue_bf16
	v_add_u32_e32 v2, s41, v186
	v_ashrrev_i32_e32 v3, 31, v2
	v_lshlrev_b64 v[2:3], 11, v[2:3]
	v_lshl_or_b32 v2, v242, 2, v2
	v_lshl_add_u64 v[4:5], s[24:25], 0, v[2:3]
	v_lshl_add_u64 v[2:3], s[26:27], 0, v[2:3]
	global_load_dwordx4 v[120:123], v[4:5], off offset:384 nt
	global_load_dwordx4 v[124:127], v[4:5], off offset:256 nt
	global_load_dwordx4 v[112:115], v[4:5], off offset:128 nt
	global_load_dwordx4 v[116:119], v[4:5], off nt
	global_load_dwordx4 v[132:135], v[2:3], off offset:384 nt
	global_load_dwordx4 v[140:143], v[2:3], off offset:256 nt
	global_load_dwordx4 v[128:131], v[2:3], off offset:128 nt
	global_load_dwordx4 v[136:139], v[2:3], off nt
	s_branch .Ls2_issue_done

.Ls2_issue_odd:
	v_add_u32_e32 v2, s41, v186
	v_ashrrev_i32_e32 v3, 31, v2
	v_lshlrev_b64 v[2:3], 11, v[2:3]
	v_lshl_or_b32 v2, v242, 2, v2
	v_lshl_add_u64 v[4:5], s[24:25], 0, v[2:3]
	v_lshl_add_u64 v[2:3], s[26:27], 0, v[2:3]
	global_load_dwordx4 v[218:221], v[4:5], off offset:384 nt
	global_load_dwordx4 v[222:225], v[4:5], off offset:256 nt
	global_load_dwordx4 v[210:213], v[4:5], off offset:128 nt
	global_load_dwordx4 v[214:217], v[4:5], off nt
	global_load_dwordx4 v[230:233], v[2:3], off offset:384 nt
	global_load_dwordx4 v[238:241], v[2:3], off offset:256 nt
	global_load_dwordx4 v[226:229], v[2:3], off offset:128 nt
	global_load_dwordx4 v[234:237], v[2:3], off nt
